# attention loop: the 12 xor-16/xor-32 ds_bpermute shuffles replaced by v_permlane16/32_swap + 3-way xor (no LDS round trips)
# baseline (speedup 1.0000x reference)
.LBB0_259:
	v_add_u32_e32 v68, s92, v116
	v_add_u32_e32 v70, v68, v120
	ds_read_b128 v[48:51], v70
	ds_read_b128 v[52:55], v70 offset:4096
	ds_read_b128 v[56:59], v70 offset:8192
	ds_read_b128 v[94:97], v70 offset:12288
	v_add_u32_e32 v70, v68, v121
	v_add_u32_e32 v71, v68, v122
	ds_read_b128 v[174:177], v71 offset:12288
	v_add_u32_e32 v68, v68, v123
	ds_read_b128 v[178:181], v68 offset:12288
	s_waitcnt lgkmcnt(0)
	v_mfma_f32_16x16x32_bf16 v[52:55], v[52:55], v[0:3], 0
	v_mfma_f32_16x16x32_bf16 v[98:101], v[56:59], v[0:3], 0
	ds_read_b128 v[56:59], v70 offset:12288
	v_mfma_f32_16x16x32_bf16 v[94:97], v[94:97], v[0:3], 0
	s_waitcnt lgkmcnt(0)
	v_mfma_f32_16x16x32_bf16 v[56:59], v[56:59], v[4:7], v[94:97]
	s_nop 5
	ds_read_b128 v[94:97], v70 offset:8192
	ds_read_b128 v[182:185], v71 offset:8192
	ds_read_b128 v[186:189], v68 offset:8192
	v_mfma_f32_16x16x32_bf16 v[56:59], v[174:177], v[8:11], v[56:59]
	ds_read_b128 v[174:177], v70
	ds_read_b128 v[190:193], v70 offset:4096
	ds_read_b128 v[194:197], v71
	ds_read_b128 v[198:201], v71 offset:4096
	v_mfma_f32_16x16x32_bf16 v[56:59], v[178:181], v[12:15], v[56:59]
	ds_read_b128 v[178:181], v68
	ds_read_b128 v[202:205], v68 offset:4096
	s_waitcnt lgkmcnt(0)
	v_mfma_f32_16x16x32_bf16 v[94:97], v[94:97], v[4:7], v[98:101]
	s_nop 3
	v_exp_f32_e64 v70, -|v56|
	v_exp_f32_e64 v73, -|v57|
	v_max_f32_e32 v68, v56, v56
	v_mfma_f32_16x16x32_bf16 v[48:51], v[48:51], v[0:3], 0
	v_add_f32_e32 v70, 1.0, v70
	v_log_f32_e32 v70, v70
	v_max_f32_e32 v68, 0, v68
	v_mfma_f32_16x16x32_bf16 v[94:97], v[182:185], v[8:11], v[94:97]
	v_add_f32_e32 v68, v68, v70
	v_max_f32_e32 v70, v57, v57
	v_mfma_f32_16x16x32_bf16 v[52:55], v[190:193], v[4:7], v[52:55]
	v_max_f32_e32 v71, 0, v70
	v_add_f32_e32 v70, 1.0, v73
	v_max_f32_e32 v73, v58, v58
	v_mfma_f32_16x16x32_bf16 v[48:51], v[174:177], v[4:7], v[48:51]
	v_max_f32_e32 v193, 0, v73
	v_max_f32_e32 v73, v59, v59
	v_max_f32_e32 v183, 0, v73
	v_mfma_f32_16x16x32_bf16 v[174:177], v[186:189], v[12:15], v[94:97]
	v_log_f32_e32 v191, v70
	v_exp_f32_e64 v70, -|v58|
	v_mfma_f32_16x16x32_bf16 v[52:55], v[198:201], v[8:11], v[52:55]
	v_add_u32_e32 v198, s90, v159
	s_nop 3
	v_exp_f32_e64 v73, -|v174|
	v_exp_f32_e64 v94, -|v175|
	v_mfma_f32_16x16x32_bf16 v[52:55], v[202:205], v[12:15], v[52:55]
	v_exp_f32_e64 v96, -|v177|
	v_add_f32_e32 v73, 1.0, v73
	v_log_f32_e32 v190, v73
	v_max_f32_e32 v73, v175, v175
	v_max_f32_e32 v192, 0, v73
	v_add_f32_e32 v73, 1.0, v94
	v_exp_f32_e64 v94, -|v176|
	s_nop 0
	v_exp_f32_e64 v97, -|v52|
	v_add_f32_e32 v96, 1.0, v96
	v_mfma_f32_16x16x32_bf16 v[48:51], v[194:197], v[8:11], v[48:51]
	v_log_f32_e32 v194, v73
	v_max_f32_e32 v73, v176, v176
	v_log_f32_e32 v96, v96
	v_max_f32_e32 v182, 0, v73
	v_add_f32_e32 v73, 1.0, v94
	v_add_f32_e32 v97, 1.0, v97
	v_log_f32_e32 v94, v73
	v_max_f32_e32 v73, v177, v177
	v_log_f32_e32 v97, v97
	v_max_f32_e32 v73, 0, v73
	v_add_f32_e32 v185, v73, v96
	v_max_f32_e32 v73, v52, v52
	v_exp_f32_e64 v96, -|v54|
	v_max_f32_e32 v73, 0, v73
	v_add_f32_e32 v97, v73, v97
	v_exp_f32_e64 v73, -|v53|
	v_add_f32_e32 v96, 1.0, v96
	v_mfma_f32_16x16x32_bf16 v[48:51], v[178:181], v[12:15], v[48:51]
	v_log_f32_e32 v96, v96
	v_add_f32_e32 v73, 1.0, v73
	v_log_f32_e32 v181, v73
	v_max_f32_e32 v73, v54, v54
	v_max_f32_e32 v73, 0, v73
	v_add_f32_e32 v196, v73, v96
	s_nop 1
	v_exp_f32_e64 v96, -|v48|
	v_exp_f32_e64 v73, -|v55|
	v_exp_f32_e64 v100, -|v50|
	v_add_f32_e32 v70, 1.0, v70
	v_add_f32_e32 v96, 1.0, v96
	v_log_f32_e32 v96, v96
	v_add_f32_e32 v73, 1.0, v73
	v_log_f32_e32 v180, v73
	v_max_f32_e32 v73, v48, v48
	v_max_f32_e32 v73, 0, v73
	v_add_f32_e32 v73, v73, v96
	v_exp_f32_e64 v96, -|v49|
	v_max_f32_e32 v98, v53, v53
	v_log_f32_e32 v195, v70
	v_exp_f32_e64 v70, -|v59|
	v_add_f32_e32 v96, 1.0, v96
	v_log_f32_e32 v101, v96
	v_add_f32_e32 v96, 1.0, v100
	v_max_f32_e32 v179, 0, v98
	v_max_f32_e32 v98, v55, v55
	v_log_f32_e32 v96, v96
	v_max_f32_e32 v178, 0, v98
	v_max_f32_e32 v98, v49, v49
	v_exp_f32_e64 v100, -|v51|
	v_max_f32_e32 v99, 0, v98
	v_max_f32_e32 v98, v50, v50
	v_max_f32_e32 v98, 0, v98
	v_add_f32_e32 v70, 1.0, v70
	v_add_f32_e32 v197, v98, v96
	v_max_f32_e32 v96, v51, v51
	v_log_f32_e32 v95, v70
	v_max_f32_e32 v98, 0, v96
	v_add_f32_e32 v96, 1.0, v100
	v_cmp_lt_u32_e64 s[12:13], v198, v60
	v_max_f32_e32 v70, v174, v174
	v_log_f32_e32 v100, v96
	v_cndmask_b32_e64 v96, 0, -v73, s[12:13]
	v_or_b32_e32 v73, 48, v198
	v_max_f32_e32 v70, 0, v70
	v_or_b32_e32 v188, 33, v198
	v_or_b32_e32 v189, 32, v198
	v_or_b32_e32 v201, 49, v198
	v_cmp_lt_u32_e64 s[14:15], v73, v60
	v_or_b32_e32 v204, 50, v198
	v_pk_add_f32 v[70:71], v[70:71], v[190:191]
	v_cndmask_b32_e64 v184, 0, -v68, s[14:15]
	v_pk_add_f32 v[186:187], v[192:193], v[194:195]
	v_cmp_lt_u32_e64 s[16:17], v204, v60
	v_cmp_lt_u32_e32 vcc, v188, v61
	v_cmp_lt_u32_e64 s[18:19], v201, v61
	v_cmp_lt_u32_e64 s[8:9], v189, v60
	v_add_f32_e32 v73, 0, v184
	v_or_b32_e32 v202, 34, v198
	v_or_b32_e32 v203, 51, v198
	v_pk_add_f32 v[94:95], v[182:183], v[94:95]
	v_cndmask_b32_e64 v183, 0, -v187, s[16:17]
	v_cndmask_b32_e64 v182, 0, -v186, vcc
	v_cndmask_b32_e64 v187, 0, -v71, s[18:19]
	v_cndmask_b32_e64 v186, 0, -v70, s[8:9]
	v_pk_add_f32 v[70:71], v[186:187], v[72:73]
	v_cmp_lt_u32_e64 s[24:25], v203, v61
	v_cmp_lt_u32_e64 s[20:21], v202, v60
	v_pk_add_f32 v[70:71], v[182:183], v[70:71]
	v_cndmask_b32_e64 v189, 0, -v95, s[24:25]
	v_cndmask_b32_e64 v188, 0, -v94, s[20:21]
	v_pk_add_f32 v[70:71], v[188:189], v[70:71]
	v_mov_b32_e32 v160, v71
	v_mov_b32_e32 v95, v71
	s_nop 1
	v_permlane16_swap_b32_e32 v160, v95
	v_bitop3_b32 v95, v160, v95, v71 bitop3:0x96
	v_or_b32_e32 v68, 35, v198
	v_cmp_lt_u32_e64 s[10:11], v68, v61
	v_mov_b32_e32 v161, v71
	v_mov_b32_e32 v191, v71
	s_nop 1
	v_permlane32_swap_b32_e32 v161, v191
	v_bitop3_b32 v191, v161, v191, v71 bitop3:0x96
	v_add_f32_e32 v201, v176, v188
	v_cndmask_b32_e64 v94, 0, -v185, s[10:11]
	s_waitcnt lgkmcnt(0)
	v_pk_add_f32 v[70:71], v[94:95], v[70:71]
	v_mov_b32_e32 v160, v70
	v_mov_b32_e32 v190, v70
	s_nop 1
	v_permlane16_swap_b32_e32 v160, v190
	v_bitop3_b32 v190, v160, v190, v70 bitop3:0x96
	v_mov_b32_e32 v161, v95
	v_mov_b32_e32 v193, v95
	s_nop 1
	v_permlane32_swap_b32_e32 v161, v193
	v_bitop3_b32 v193, v161, v193, v95 bitop3:0x96
	v_mov_b32_e32 v160, v70
	v_mov_b32_e32 v192, v70
	s_nop 1
	v_permlane32_swap_b32_e32 v160, v192
	v_bitop3_b32 v192, v160, v192, v70 bitop3:0x96
	v_add_f32_e32 v185, v58, v183
	v_cndmask_b32_e64 v58, 0, v95, s[0:1]
	s_waitcnt lgkmcnt(0)
	v_mov_b32_e32 v161, v190
	v_mov_b32_e32 v68, v190
	s_nop 1
	v_permlane32_swap_b32_e32 v161, v68
	v_bitop3_b32 v68, v161, v68, v190 bitop3:0x96
	v_pk_add_f32 v[70:71], v[70:71], v[190:191]
	v_cndmask_b32_e64 v73, 0, v190, s[0:1]
	v_cndmask_b32_e64 v95, 0, v192, s[22:23]
	v_pk_add_f32 v[70:71], v[70:71], v[192:193]
	v_add_f32_e32 v73, v73, v95
	s_waitcnt lgkmcnt(0)
	v_cndmask_b32_e64 v95, 0, v68, s[4:5]
	v_pk_add_f32 v[194:195], v[70:71], v[68:69]
	v_cndmask_b32_e64 v68, 0, v191, s[22:23]
	v_add_f32_e32 v58, v58, v68
	v_cndmask_b32_e64 v68, 0, v193, s[4:5]
	v_mov_b32_e32 v70, v188
	v_add_f32_e32 v188, v58, v68
	v_mov_b32_e32 v58, v69
	v_pk_add_f32 v[58:59], v[58:59], v[188:189]
	v_add_f32_e32 v202, v177, v94
	v_pk_add_f32 v[176:177], v[72:73], v[94:95]
	v_mov_b32_e32 v71, v195
	v_add_f32_e32 v68, v58, v59
	v_pk_add_f32 v[70:71], v[70:71], v[176:177]
	v_add_f32_e32 v68, 0, v68
	v_add_f32_e32 v204, v175, v182
	v_mov_b32_e32 v94, v182
	v_mov_b32_e32 v95, v174
	v_mov_b32_e32 v174, v70
	v_mov_b32_e32 v175, v186
	v_exp_f32_e32 v177, v68
	v_mov_b32_e32 v68, v189
	v_mov_b32_e32 v69, v57
	v_mov_b32_e32 v73, v187
	v_pk_add_f32 v[94:95], v[94:95], v[174:175]
	v_pk_add_f32 v[68:69], v[68:69], v[72:73]
	v_pk_mov_b32 v[174:175], v[182:183], v[58:59] op_sel:[1,0]
	v_add_f32_e32 v186, v58, v185
	v_pk_add_f32 v[174:175], v[174:175], v[68:69]
	v_mov_b32_e32 v57, v187
	v_mov_b32_e32 v185, v174
	v_pk_add_f32 v[56:57], v[56:57], v[184:185]
	v_add_f32_e32 v59, v68, v186
	v_add_f32_e32 v56, v58, v56
	v_add_f32_e32 v56, v56, v57
	v_exp_f32_e32 v56, v56
	v_exp_f32_e32 v59, v59
	v_add_f32_e32 v68, v174, v175
	v_exp_f32_e32 v68, v68
	v_cndmask_b32_e64 v187, 0, v56, s[14:15]
	v_add_f32_e32 v56, v201, v71
	v_add_f32_e32 v56, v176, v56
	v_exp_f32_e32 v56, v56
	v_add_f32_e32 v57, v202, v71
	v_add_f32_e32 v57, 0, v57
	v_or_b32_e32 v58, 2, v198
	v_cndmask_b32_e64 v189, 0, v56, s[20:21]
	v_or_b32_e32 v56, 16, v198
	v_cndmask_b32_e64 v185, 0, v59, s[16:17]
	v_exp_f32_e32 v188, v57
	v_or_b32_e32 v57, 17, v198
	v_cmp_lt_u32_e64 s[16:17], v56, v60
	v_cmp_lt_u32_e64 s[14:15], v58, v60
	v_cndmask_b32_e64 v186, 0, v68, s[18:19]
	v_cndmask_b32_e64 v56, 0, -v97, s[16:17]
	v_cndmask_b32_e64 v58, 0, -v197, s[14:15]
	v_or_b32_e32 v68, 18, v198
	v_pk_add_f32 v[174:175], v[178:179], v[180:181]
	v_cmp_lt_u32_e64 s[20:21], v57, v61
	v_add_f32_e32 v59, 0, v56
	v_add_f32_e32 v191, v50, v58
	v_or_b32_e32 v50, 19, v198
	v_cmp_lt_u32_e64 s[18:19], v68, v60
	v_cndmask_b32_e64 v175, 0, -v175, s[20:21]
	v_cndmask_b32_e64 v184, 0, v177, s[24:25]
	v_cndmask_b32_e64 v68, 0, -v196, s[18:19]
	v_cmp_lt_u32_e64 s[24:25], v50, v61
	v_add_f32_e32 v50, v175, v59
	v_add_f32_e32 v50, v68, v50
	v_cndmask_b32_e64 v174, 0, -v174, s[24:25]
	v_add_f32_e32 v50, v174, v50
	v_mov_b32_e32 v160, v50
	v_mov_b32_e32 v57, v50
	s_nop 1
	v_permlane16_swap_b32_e32 v160, v57
	v_bitop3_b32 v57, v160, v57, v50 bitop3:0x96
	v_mov_b32_e32 v161, v50
	v_mov_b32_e32 v176, v50
	s_nop 1
	v_permlane32_swap_b32_e32 v161, v176
	v_bitop3_b32 v176, v161, v176, v50 bitop3:0x96
	v_mov_b32_e32 v73, v53
	v_mov_b32_e32 v181, v194
	v_mov_b32_e32 v183, v195
	s_waitcnt lgkmcnt(0)
	v_mov_b32_e32 v160, v57
	v_mov_b32_e32 v177, v57
	s_nop 1
	v_permlane32_swap_b32_e32 v160, v177
	v_bitop3_b32 v177, v160, v177, v57 bitop3:0x96
	v_add_f32_e32 v50, v50, v57
	v_add_f32_e32 v179, v50, v176
	v_cndmask_b32_e64 v50, 0, v57, s[0:1]
	v_cndmask_b32_e64 v53, 0, v176, s[22:23]
	v_add_f32_e32 v180, v50, v53
	s_waitcnt lgkmcnt(0)
	v_cndmask_b32_e64 v182, 0, v177, s[4:5]
	v_pk_add_f32 v[180:181], v[180:181], v[182:183]
	v_add_f32_e32 v69, v54, v68
	v_mov_b32_e32 v53, v180
	v_mov_b32_e32 v57, v181
	v_add_f32_e32 v59, v55, v174
	v_pk_add_f32 v[52:53], v[52:53], v[56:57]
	v_pk_add_f32 v[54:55], v[72:73], v[174:175]
	v_add_f32_e32 v50, v59, v53
	v_add_f32_e32 v56, v69, v53
	v_add_f32_e32 v50, 0, v50
	v_add_f32_e32 v56, v54, v56
	v_exp_f32_e32 v56, v56
	v_exp_f32_e32 v50, v50
	v_mov_b32_e32 v69, v53
	v_add_u32_e32 v199, 1, v198
	v_pk_add_f32 v[54:55], v[68:69], v[54:55]
	v_or_b32_e32 v97, 3, v198
	v_cndmask_b32_e64 v68, 0, v56, s[18:19]
	v_cndmask_b32_e64 v69, 0, v50, s[24:25]
	v_add_f32_e32 v50, v54, v55
	v_add_f32_e32 v55, v52, v53
	v_pk_add_f32 v[52:53], v[98:99], v[100:101]
	v_cmp_lt_u32_e64 s[18:19], v199, v61
	v_add_f32_e32 v200, 0, v96
	v_cmp_lt_u32_e64 s[24:25], v97, v61
	v_cndmask_b32_e64 v57, 0, -v53, s[18:19]
	v_exp_f32_e32 v50, v50
	v_cndmask_b32_e64 v56, 0, -v52, s[24:25]
	v_add_f32_e32 v52, v57, v200
	v_add_f32_e32 v52, v58, v52
	v_add_f32_e32 v182, v56, v52
	v_mov_b32_e32 v161, v182
	v_mov_b32_e32 v183, v182
	s_nop 1
	v_permlane16_swap_b32_e32 v161, v183
	v_bitop3_b32 v183, v161, v183, v182 bitop3:0x96
	v_add_f32_e32 v52, v175, v54
	v_mov_b32_e32 v160, v182
	v_mov_b32_e32 v192, v182
	s_nop 1
	v_permlane32_swap_b32_e32 v160, v192
	v_bitop3_b32 v192, v160, v192, v182 bitop3:0x96
	v_add_f32_e32 v52, v52, v55
	v_exp_f32_e32 v52, v52
	s_waitcnt lgkmcnt(0)
	v_mov_b32_e32 v161, v183
	v_mov_b32_e32 v193, v183
	s_nop 1
	v_permlane32_swap_b32_e32 v161, v193
	v_bitop3_b32 v193, v161, v193, v183 bitop3:0x96
	v_cndmask_b32_e64 v178, 0, v183, s[0:1]
	v_cndmask_b32_e64 v176, 0, v192, s[22:23]
	v_cndmask_b32_e64 v99, 0, v52, s[16:17]
	v_pk_add_f32 v[52:53], v[178:179], v[176:177]
	s_waitcnt lgkmcnt(0)
	v_cndmask_b32_e64 v180, 0, v193, s[4:5]
	v_pk_add_f32 v[52:53], v[52:53], v[180:181]
	v_mov_b32_e32 v73, v49
	v_mov_b32_e32 v49, v52
	v_mov_b32_e32 v97, v53
	v_pk_add_f32 v[48:49], v[48:49], v[96:97]
	v_cndmask_b32_e64 v98, 0, v50, s[20:21]
	v_add_f32_e32 v100, v51, v56
	v_pk_add_f32 v[50:51], v[72:73], v[56:57]
	v_mov_b32_e32 v59, v49
	v_pk_add_f32 v[54:55], v[58:59], v[50:51]
	v_add_f32_e32 v51, v100, v49
	v_add_f32_e32 v52, v191, v49
	v_add_f32_e32 v48, v48, v49
	v_add_f32_e32 v49, v57, v54
	v_add_f32_e32 v51, 0, v51
	v_add_f32_e32 v50, v50, v52
	v_add_f32_e32 v52, v54, v55
	v_add_f32_e32 v48, v49, v48
	v_exp_f32_e32 v51, v51
	v_exp_f32_e32 v50, v50
	v_exp_f32_e32 v52, v52
	v_exp_f32_e32 v48, v48
	v_bfe_u32 v59, v68, 16, 1
	v_cndmask_b32_e64 v49, 0, v50, s[14:15]
	v_cndmask_b32_e64 v50, 0, v51, s[24:25]
	v_cndmask_b32_e64 v51, 0, v52, s[18:19]
	v_cndmask_b32_e64 v48, 0, v48, s[12:13]
	v_add_u32_e32 v52, s92, v75
	v_bfe_u32 v56, v48, 16, 1
	v_bfe_u32 v57, v51, 16, 1
	v_bfe_u32 v73, v50, 16, 1
	v_bfe_u32 v96, v49, 16, 1
	v_add3_u32 v59, v68, v59, s84
	v_add3_u32 v68, v52, v124, v117
	v_add3_u32 v191, v52, v125, v117
	v_add3_u32 v97, v51, v57, s84
	v_add3_u32 v100, v48, v56, s84
	v_add3_u32 v101, v49, v96, s84
	v_add3_u32 v73, v50, v73, s84
	ds_read2st64_b64 v[48:51], v68 offset0:32 offset1:36
	ds_read2st64_b64 v[54:57], v191 offset0:32 offset1:36
	v_bfe_u32 v58, v69, 16, 1
	v_add3_u32 v58, v69, v58, s84
	v_cvt_pk_bf16_f32 v98, v99, v98
	s_waitcnt lgkmcnt(0)
	v_mov_b32_e32 v174, v48
	v_mov_b32_e32 v175, v49
	v_mov_b32_e32 v176, v54
	v_mov_b32_e32 v177, v55
	v_perm_b32 v96, v97, v100, s85
	v_perm_b32 v99, v58, v59, s85
	v_perm_b32 v97, v73, v101, s85
	ds_read2st64_b64 v[178:181], v68 offset0:40 offset1:44
	v_mov_b32_e32 v54, v50
	v_mfma_f32_16x16x32_bf16 v[16:19], v[174:177], v[96:99], v[16:19]
	ds_read2st64_b64 v[174:177], v191 offset0:40 offset1:44
	v_mov_b32_e32 v55, v51
	s_waitcnt lgkmcnt(0)
	v_mov_b32_e32 v48, v178
	v_mov_b32_e32 v49, v179
	v_add_f32_e32 v190, v204, v71
	v_mov_b32_e32 v50, v174
	v_mov_b32_e32 v51, v175
	v_mfma_f32_16x16x32_bf16 v[20:23], v[54:57], v[96:99], v[20:23]
	v_add_f32_e32 v54, v70, v190
	v_exp_f32_e32 v58, v54
	ds_read2st64_b64 v[54:57], v68 offset0:48 offset1:52
	v_mfma_f32_16x16x32_bf16 v[24:27], v[48:51], v[96:99], v[24:27]
	ds_read2st64_b64 v[48:51], v191 offset0:48 offset1:52
	v_mov_b32_e32 v174, v180
	v_mov_b32_e32 v175, v181
	s_waitcnt lgkmcnt(0)
	v_mov_b32_e32 v178, v54
	v_mov_b32_e32 v179, v55
	v_mov_b32_e32 v180, v48
	v_add_f32_e32 v48, v95, v71
	v_mov_b32_e32 v181, v49
	v_mfma_f32_16x16x32_bf16 v[32:35], v[174:177], v[96:99], v[32:35]
	v_add_f32_e32 v59, v94, v48
	ds_read2st64_b64 v[68:71], v68 offset0:56 offset1:60
	ds_read2st64_b64 v[174:177], v191 offset0:56 offset1:60
	v_mov_b32_e32 v48, v56
	v_mov_b32_e32 v49, v57
	v_mfma_f32_16x16x32_bf16 v[28:31], v[178:181], v[96:99], v[28:31]
	s_waitcnt lgkmcnt(0)
	v_mov_b32_e32 v54, v68
	v_mov_b32_e32 v55, v69
	v_mov_b32_e32 v56, v174
	v_mov_b32_e32 v57, v175
	v_mfma_f32_16x16x32_bf16 v[36:39], v[48:51], v[96:99], v[36:39]
	v_exp_f32_e32 v48, v59
	v_mov_b32_e32 v174, v70
	v_mov_b32_e32 v175, v71
	v_cndmask_b32_e64 v49, 0, v188, s[10:11]
	v_cndmask_b32_e32 v50, 0, v58, vcc
	v_cndmask_b32_e64 v48, 0, v48, s[8:9]
	v_mfma_f32_16x16x32_bf16 v[40:43], v[54:57], v[96:99], v[40:43]
	v_bfe_u32 v51, v48, 16, 1
	v_bfe_u32 v54, v50, 16, 1
	v_bfe_u32 v55, v49, 16, 1
	v_mfma_f32_16x16x32_bf16 v[44:47], v[174:177], v[96:99], v[44:47]
	v_bfe_u32 v56, v189, 16, 1
	v_add3_u32 v174, v52, v126, v117
	v_add3_u32 v52, v52, v127, v117
	v_add3_u32 v69, v50, v54, s84
	v_add3_u32 v70, v48, v51, s84
	v_add3_u32 v73, v189, v56, s84
	v_add3_u32 v95, v49, v55, s84
	ds_read2st64_b64 v[48:51], v174 offset0:32 offset1:36
	ds_read2st64_b64 v[54:57], v52 offset0:32 offset1:36
	v_perm_b32 v94, v69, v70, s85
	s_waitcnt lgkmcnt(0)
	v_mov_b32_e32 v68, v48
	v_mov_b32_e32 v69, v49
	v_mov_b32_e32 v70, v54
	v_mov_b32_e32 v71, v55
	v_perm_b32 v95, v95, v73, s85
	v_cvt_pk_bf16_f32 v96, v187, v186
	v_cvt_pk_bf16_f32 v97, v185, v184
	ds_read2st64_b64 v[98:101], v174 offset0:40 offset1:44
	v_mov_b32_e32 v54, v50
	v_mfma_f32_16x16x32_bf16 v[16:19], v[68:71], v[94:97], v[16:19]
	ds_read2st64_b64 v[68:71], v52 offset0:40 offset1:44
	v_mov_b32_e32 v55, v51
	s_waitcnt lgkmcnt(0)
	v_mov_b32_e32 v48, v98
	v_mov_b32_e32 v49, v99
	v_mfma_f32_16x16x32_bf16 v[20:23], v[54:57], v[94:97], v[20:23]
	v_mov_b32_e32 v50, v68
	v_mov_b32_e32 v51, v69
	v_add_f32_e32 v54, v182, v183
	v_add_f32_e32 v58, v54, v192
	ds_read2st64_b64 v[54:57], v174 offset0:48 offset1:52
	v_mov_b32_e32 v68, v100
	v_mov_b32_e32 v69, v101
	v_mfma_f32_16x16x32_bf16 v[24:27], v[48:51], v[94:97], v[24:27]
	ds_read2st64_b64 v[48:51], v52 offset0:48 offset1:52
	s_waitcnt lgkmcnt(0)
	v_mov_b32_e32 v98, v54
	v_add_f32_e32 v54, v58, v193
	v_mfma_f32_16x16x32_bf16 v[32:35], v[68:71], v[94:97], v[32:35]
	v_add_f32_e32 v69, v54, v53
	v_mov_b32_e32 v100, v48
	v_mov_b32_e32 v48, v56
	v_mov_b32_dpp v56, v69 quad_perm:[1,0,3,2] row_mask:0xf bank_mask:0xf
	v_mov_b32_e32 v101, v49
	v_mov_b32_e32 v49, v57
	v_mov_b32_e32 v99, v55
	s_waitcnt lgkmcnt(0)
	v_max_f32_e32 v56, v56, v56
	v_max_f32_e32 v68, v69, v56
	s_nop 1
	v_mov_b32_dpp v70, v68 quad_perm:[2,3,0,1] row_mask:0xf bank_mask:0xf
	v_mfma_f32_16x16x32_bf16 v[36:39], v[48:51], v[94:97], v[36:39]
	ds_read2st64_b64 v[48:51], v174 offset0:56 offset1:60
	ds_read2st64_b64 v[52:55], v52 offset0:56 offset1:60
	s_waitcnt lgkmcnt(0)
	v_mov_b32_e32 v56, v48
	v_max_f32_e32 v48, v70, v70
	v_max_f32_e32 v48, v68, v48
	v_mov_b32_e32 v57, v49
	s_nop 0
	v_mov_b32_dpp v49, v48 row_half_mirror row_mask:0xf bank_mask:0xf
	v_mov_b32_e32 v58, v52
	v_mov_b32_e32 v59, v53
	v_mov_b32_e32 v52, v50
	v_mov_b32_e32 v53, v51
	s_waitcnt lgkmcnt(0)
	v_max_f32_e32 v49, v49, v49
	v_max_f32_e32 v48, v48, v49
	s_nop 1
	v_mov_b32_dpp v49, v48 row_mirror row_mask:0xf bank_mask:0xf
	v_mfma_f32_16x16x32_bf16 v[28:31], v[98:101], v[94:97], v[28:31]
	v_mfma_f32_16x16x32_bf16 v[40:43], v[56:59], v[94:97], v[40:43]
	v_mfma_f32_16x16x32_bf16 v[44:47], v[52:55], v[94:97], v[44:47]
	s_and_saveexec_b64 s[8:9], s[6:7]
	s_cbranch_execz .LBB0_256
	s_waitcnt lgkmcnt(0)
	v_max_f32_e32 v49, v49, v49
	v_max_f32_e32 v48, v48, v48
	v_max_f32_e32 v48, v48, v49
	ds_write_b32 v119, v48
	s_branch .LBB0_256
